# v082: v081 + the same nt hint on the cache stores of the prologue gather (half A)
# baseline (speedup 1.0000x reference)
.LBB0_261:
	s_waitcnt lgkmcnt(0)
	v_add_co_u32_e32 v38, vcc, 0xffffc000, v86
	v_lshl_add_u64 v[92:93], s[34:35], 0, v[88:89]
	s_nop 0
	v_addc_co_u32_e32 v39, vcc, -1, v87, vcc
	global_load_dwordx4 v[70:73], v[38:39], off offset:-1024 nt
	global_load_dwordx4 v[66:69], v[38:39], off nt
	v_add_co_u32_e32 v38, vcc, 0xffffd000, v86
	s_waitcnt vmcnt(10)
	v_cvt_pk_bf16_f32 v94, v2, v3
	v_addc_co_u32_e32 v39, vcc, -1, v87, vcc
	global_load_dwordx4 v[62:65], v[38:39], off offset:-3072 nt
	global_load_dwordx4 v[58:61], v[38:39], off offset:-2048 nt
	global_load_dwordx4 v[54:57], v[38:39], off offset:-1024 nt
	global_load_dwordx4 v[50:53], v[38:39], off nt
	v_add_co_u32_e32 v38, vcc, 0xffffe000, v86
	v_cvt_pk_bf16_f32 v95, v4, v5
	s_nop 0
	v_addc_co_u32_e32 v39, vcc, -1, v87, vcc
	global_load_dwordx4 v[46:49], v[38:39], off offset:-3072 nt
	global_load_dwordx4 v[42:45], v[38:39], off offset:-2048 nt
	s_nop 0
	global_load_dwordx4 v[38:41], v[38:39], off offset:-1024 nt
	v_add_co_u32_e32 v96, vcc, 0x1d123000, v92
	s_waitcnt vmcnt(14)
	v_cvt_pk_bf16_f32 v98, v14, v15
	v_addc_co_u32_e32 v97, vcc, 0, v93, vcc
	global_store_dwordx2 v[96:97], v[94:95], off offset:3072 nt
	v_cvt_pk_bf16_f32 v94, v6, v7
	v_cvt_pk_bf16_f32 v95, v8, v9
	v_and_b32_e32 v75, 0xffff0000, v94
	global_store_dwordx2 v[96:97], v[94:95], off offset:3584 nt
	v_lshlrev_b32_e32 v1, 16, v94
	v_mul_f32_e32 v75, v75, v75
	v_and_b32_e32 v94, 0xffff0000, v95
	v_fmac_f32_e32 v75, v1, v1
	v_lshlrev_b32_e32 v1, 16, v95
	v_mul_f32_e32 v94, v94, v94
	v_fmac_f32_e32 v94, v1, v1
	v_add_f32_e32 v1, v75, v94
	v_cvt_pk_bf16_f32 v94, v10, v11
	v_cvt_pk_bf16_f32 v95, v12, v13
	v_and_b32_e32 v96, 0xffff0000, v94
	v_lshlrev_b32_e32 v75, 16, v94
	v_mul_f32_e32 v96, v96, v96
	v_and_b32_e32 v97, 0xffff0000, v95
	v_fmac_f32_e32 v96, v75, v75
	v_lshlrev_b32_e32 v75, 16, v95
	v_mul_f32_e32 v97, v97, v97
	v_fmac_f32_e32 v97, v75, v75
	v_cndmask_b32_e64 v1, 0, v1, s[8:9]
	v_add_f32_e32 v75, v96, v97
	v_cvt_pk_bf16_f32 v99, v16, v17
	v_and_b32_e32 v96, 0xffff0000, v98
	v_cndmask_b32_e64 v1, v1, v75, s[10:11]
	v_lshlrev_b32_e32 v75, 16, v98
	v_mul_f32_e32 v96, v96, v96
	v_and_b32_e32 v97, 0xffff0000, v99
	v_fmac_f32_e32 v96, v75, v75
	v_lshlrev_b32_e32 v75, 16, v99
	v_mul_f32_e32 v97, v97, v97
	v_fmac_f32_e32 v97, v75, v75
	s_waitcnt vmcnt(15)
	v_cvt_pk_bf16_f32 v100, v18, v19
	v_add_f32_e32 v75, v96, v97
	v_cvt_pk_bf16_f32 v101, v20, v21
	v_and_b32_e32 v96, 0xffff0000, v100
	v_cndmask_b32_e64 v1, v1, v75, s[12:13]
	v_lshlrev_b32_e32 v75, 16, v100
	v_mul_f32_e32 v96, v96, v96
	v_and_b32_e32 v97, 0xffff0000, v101
	v_fmac_f32_e32 v96, v75, v75
	v_lshlrev_b32_e32 v75, 16, v101
	v_mul_f32_e32 v97, v97, v97
	v_fmac_f32_e32 v97, v75, v75
	s_waitcnt vmcnt(14)
	v_cvt_pk_bf16_f32 v102, v22, v23
	v_add_f32_e32 v75, v96, v97
	v_cvt_pk_bf16_f32 v103, v24, v25
	v_and_b32_e32 v96, 0xffff0000, v102
	v_cndmask_b32_e64 v1, v1, v75, s[14:15]
	v_lshlrev_b32_e32 v75, 16, v102
	v_mul_f32_e32 v96, v96, v96
	v_and_b32_e32 v97, 0xffff0000, v103
	v_fmac_f32_e32 v96, v75, v75
	v_lshlrev_b32_e32 v75, 16, v103
	v_mul_f32_e32 v97, v97, v97
	v_fmac_f32_e32 v97, v75, v75
	s_waitcnt vmcnt(13)
	v_cvt_pk_bf16_f32 v104, v26, v27
	v_add_f32_e32 v75, v96, v97
	v_cvt_pk_bf16_f32 v105, v28, v29
	v_and_b32_e32 v96, 0xffff0000, v104
	v_cndmask_b32_e64 v1, v1, v75, s[16:17]
	v_lshlrev_b32_e32 v75, 16, v104
	v_mul_f32_e32 v96, v96, v96
	v_and_b32_e32 v97, 0xffff0000, v105
	v_fmac_f32_e32 v96, v75, v75
	v_lshlrev_b32_e32 v75, 16, v105
	v_mul_f32_e32 v97, v97, v97
	v_fmac_f32_e32 v97, v75, v75
	s_waitcnt vmcnt(12)
	v_cvt_pk_bf16_f32 v106, v30, v31
	v_add_f32_e32 v75, v96, v97
	v_cvt_pk_bf16_f32 v107, v32, v33
	v_and_b32_e32 v96, 0xffff0000, v106
	v_cndmask_b32_e64 v1, v1, v75, s[18:19]
	v_lshlrev_b32_e32 v75, 16, v106
	v_mul_f32_e32 v96, v96, v96
	v_and_b32_e32 v97, 0xffff0000, v107
	v_fmac_f32_e32 v96, v75, v75
	v_lshlrev_b32_e32 v75, 16, v107
	v_mul_f32_e32 v97, v97, v97
	v_fmac_f32_e32 v97, v75, v75
	s_waitcnt vmcnt(11)
	v_cvt_pk_bf16_f32 v108, v34, v35
	v_add_f32_e32 v75, v96, v97
	v_cvt_pk_bf16_f32 v109, v36, v37
	v_and_b32_e32 v96, 0xffff0000, v108
	v_cndmask_b32_e64 v1, v1, v75, s[20:21]
	v_lshlrev_b32_e32 v75, 16, v108
	v_mul_f32_e32 v96, v96, v96
	v_and_b32_e32 v97, 0xffff0000, v109
	v_fmac_f32_e32 v96, v75, v75
	v_lshlrev_b32_e32 v75, 16, v109
	v_mul_f32_e32 v97, v97, v97
	v_fmac_f32_e32 v97, v75, v75
	v_add_f32_e32 v75, v96, v97
	v_cndmask_b32_e64 v1, v1, v75, s[22:23]
	ds_swizzle_b32 v75, v1 offset:swizzle(SWAP,1)
	v_add_co_u32_e32 v96, vcc, s44, v92
	s_waitcnt lgkmcnt(0)
	v_add_f32_e32 v1, v1, v75
	ds_swizzle_b32 v75, v1 offset:swizzle(SWAP,2)
	v_addc_co_u32_e32 v97, vcc, 0, v93, vcc
	global_store_dwordx2 v[96:97], v[94:95], off nt
	global_store_dwordx2 v[96:97], v[98:99], off offset:512 nt
	global_store_dwordx2 v[96:97], v[100:101], off offset:1024 nt
	global_store_dwordx2 v[96:97], v[102:103], off offset:1536 nt
	v_lshl_add_u64 v[94:95], s[34:35], 0, v[90:91]
	s_waitcnt lgkmcnt(0)
	v_add_f32_e32 v1, v1, v75
	ds_swizzle_b32 v75, v1 offset:swizzle(SWAP,4)
	global_store_dwordx2 v[96:97], v[104:105], off offset:2048 nt
	global_store_dwordx2 v[96:97], v[106:107], off offset:2560 nt
	global_store_dwordx2 v[96:97], v[108:109], off offset:3072 nt
	s_and_saveexec_b64 s[40:41], s[6:7]
	s_cbranch_execz .LBB0_263
	v_add_co_u32_e32 v98, vcc, 0x34d30000, v94
	s_waitcnt lgkmcnt(0)
	v_add_f32_e32 v1, v1, v75
	v_addc_co_u32_e32 v99, vcc, 0, v95, vcc
	global_store_dword v[98:99], v1, off

.LBB0_265:
	s_waitcnt vmcnt(16)
	v_cvt_pk_bf16_f32 v66, v66, v67
	v_cvt_pk_bf16_f32 v67, v68, v69
	v_and_b32_e32 v68, 0xffff0000, v66
	v_lshlrev_b32_e32 v1, 16, v66
	v_mul_f32_e32 v68, v68, v68
	v_and_b32_e32 v69, 0xffff0000, v67
	v_fmac_f32_e32 v68, v1, v1
	v_lshlrev_b32_e32 v1, 16, v67
	v_mul_f32_e32 v69, v69, v69
	s_waitcnt vmcnt(15)
	v_cvt_pk_bf16_f32 v62, v62, v63
	v_fmac_f32_e32 v69, v1, v1
	v_cvt_pk_bf16_f32 v63, v64, v65
	v_and_b32_e32 v65, 0xffff0000, v62
	v_add_f32_e32 v1, v68, v69
	v_lshlrev_b32_e32 v64, 16, v62
	v_mul_f32_e32 v65, v65, v65
	v_and_b32_e32 v68, 0xffff0000, v63
	v_fmac_f32_e32 v65, v64, v64
	v_lshlrev_b32_e32 v64, 16, v63
	v_mul_f32_e32 v68, v68, v68
	v_fmac_f32_e32 v68, v64, v64
	s_waitcnt vmcnt(14)
	v_cvt_pk_bf16_f32 v58, v58, v59
	v_cndmask_b32_e64 v1, 0, v1, s[8:9]
	v_add_f32_e32 v64, v65, v68
	v_cvt_pk_bf16_f32 v59, v60, v61
	v_and_b32_e32 v61, 0xffff0000, v58
	v_cndmask_b32_e64 v1, v1, v64, s[10:11]
	v_lshlrev_b32_e32 v60, 16, v58
	v_mul_f32_e32 v61, v61, v61
	v_and_b32_e32 v64, 0xffff0000, v59
	v_fmac_f32_e32 v61, v60, v60
	v_lshlrev_b32_e32 v60, 16, v59
	v_mul_f32_e32 v64, v64, v64
	v_fmac_f32_e32 v64, v60, v60
	s_waitcnt vmcnt(13)
	v_cvt_pk_bf16_f32 v54, v54, v55
	v_add_f32_e32 v60, v61, v64
	v_cvt_pk_bf16_f32 v55, v56, v57
	v_and_b32_e32 v57, 0xffff0000, v54
	v_cndmask_b32_e64 v1, v1, v60, s[12:13]
	v_lshlrev_b32_e32 v56, 16, v54
	v_mul_f32_e32 v57, v57, v57
	v_and_b32_e32 v60, 0xffff0000, v55
	v_fmac_f32_e32 v57, v56, v56
	v_lshlrev_b32_e32 v56, 16, v55
	v_mul_f32_e32 v60, v60, v60
	v_fmac_f32_e32 v60, v56, v56
	s_waitcnt vmcnt(12)
	v_cvt_pk_bf16_f32 v50, v50, v51
	v_add_f32_e32 v56, v57, v60
	v_cvt_pk_bf16_f32 v51, v52, v53
	v_and_b32_e32 v53, 0xffff0000, v50
	v_cndmask_b32_e64 v1, v1, v56, s[14:15]
	v_lshlrev_b32_e32 v52, 16, v50
	v_mul_f32_e32 v53, v53, v53
	v_and_b32_e32 v56, 0xffff0000, v51
	v_fmac_f32_e32 v53, v52, v52
	v_lshlrev_b32_e32 v52, 16, v51
	v_mul_f32_e32 v56, v56, v56
	v_fmac_f32_e32 v56, v52, v52
	s_waitcnt vmcnt(11)
	v_cvt_pk_bf16_f32 v46, v46, v47
	v_add_f32_e32 v52, v53, v56
	v_cvt_pk_bf16_f32 v47, v48, v49
	v_and_b32_e32 v49, 0xffff0000, v46
	v_cndmask_b32_e64 v1, v1, v52, s[16:17]
	v_lshlrev_b32_e32 v48, 16, v46
	v_mul_f32_e32 v49, v49, v49
	v_and_b32_e32 v52, 0xffff0000, v47
	v_fmac_f32_e32 v49, v48, v48
	v_lshlrev_b32_e32 v48, 16, v47
	v_mul_f32_e32 v52, v52, v52
	v_fmac_f32_e32 v52, v48, v48
	s_waitcnt vmcnt(10)
	v_cvt_pk_bf16_f32 v42, v42, v43
	v_add_f32_e32 v48, v49, v52
	v_cvt_pk_bf16_f32 v43, v44, v45
	v_and_b32_e32 v45, 0xffff0000, v42
	v_cndmask_b32_e64 v1, v1, v48, s[18:19]
	v_lshlrev_b32_e32 v44, 16, v42
	v_mul_f32_e32 v45, v45, v45
	v_and_b32_e32 v48, 0xffff0000, v43
	v_fmac_f32_e32 v45, v44, v44
	v_lshlrev_b32_e32 v44, 16, v43
	v_mul_f32_e32 v48, v48, v48
	v_fmac_f32_e32 v48, v44, v44
	v_add_f32_e32 v44, v45, v48
	v_cndmask_b32_e64 v1, v1, v44, s[20:21]
	s_waitcnt vmcnt(9)
	v_cvt_pk_bf16_f32 v44, v38, v39
	v_cvt_pk_bf16_f32 v45, v40, v41
	v_and_b32_e32 v39, 0xffff0000, v44
	v_lshlrev_b32_e32 v38, 16, v44
	v_mul_f32_e32 v39, v39, v39
	v_and_b32_e32 v40, 0xffff0000, v45
	v_fmac_f32_e32 v39, v38, v38
	v_lshlrev_b32_e32 v38, 16, v45
	v_mul_f32_e32 v40, v40, v40
	v_fmac_f32_e32 v40, v38, v38
	v_add_f32_e32 v38, v39, v40
	v_cndmask_b32_e64 v1, v1, v38, s[22:23]
	ds_swizzle_b32 v38, v1 offset:swizzle(SWAP,1)
	v_add_co_u32_e32 v40, vcc, s45, v92
	v_cvt_pk_bf16_f32 v70, v70, v71
	v_cvt_pk_bf16_f32 v71, v72, v73
	s_waitcnt lgkmcnt(0)
	v_add_f32_e32 v1, v1, v38
	ds_swizzle_b32 v38, v1 offset:swizzle(SWAP,2)
	v_addc_co_u32_e32 v41, vcc, 0, v93, vcc
	global_store_dwordx2 v[96:97], v[70:71], off offset:3584 nt
	global_store_dwordx2 v[40:41], v[66:67], off nt
	global_store_dwordx2 v[40:41], v[62:63], off offset:512 nt
	global_store_dwordx2 v[40:41], v[58:59], off offset:1024 nt
	global_store_dwordx2 v[40:41], v[54:55], off offset:1536 nt
	s_waitcnt lgkmcnt(0)
	v_add_f32_e32 v1, v1, v38
	ds_swizzle_b32 v38, v1 offset:swizzle(SWAP,4)
	global_store_dwordx2 v[40:41], v[50:51], off offset:2048 nt
	global_store_dwordx2 v[40:41], v[46:47], off offset:2560 nt
	global_store_dwordx2 v[40:41], v[42:43], off offset:3072 nt
	global_store_dwordx2 v[40:41], v[44:45], off offset:3584 nt
	s_and_saveexec_b64 s[42:43], s[6:7]
	s_cbranch_execz .LBB0_260
	s_waitcnt lgkmcnt(0)
	v_add_f32_e32 v1, v1, v38
	v_add_co_u32_e32 v38, vcc, 0x34d30000, v94
	s_nop 1
	v_addc_co_u32_e32 v39, vcc, 0, v95, vcc
	global_store_dword v[38:39], v1, off offset:32
	s_branch .LBB0_260
